# S5 scan stage (d): W3-fragment vmcnt waits no longer wait for the next-tile prefetch (counted +4 on has_next path; prefetch waited at its ds_write), stacked on v66
# baseline (speedup 1.0000x reference)
.LBB0_1012:
	s_waitcnt lgkmcnt(0)
	s_barrier
	ds_read_b128 v[106:109], v220 offset:13056
	ds_read_b128 v[126:129], v220 offset:13120
	ds_read_b128 v[102:105], v220
	s_waitcnt vmcnt(6) lgkmcnt(2)
	v_mfma_f32_16x16x32_bf16 v[110:113], v[38:41], v[106:109], 0
	ds_read_b128 v[98:101], v220 offset:4352
	ds_read_b128 v[114:117], v220 offset:4416
	ds_read_b128 v[86:89], v220 offset:8704
	ds_read_b128 v[122:125], v220 offset:8768
	s_cmp_lg_u64 s[28:29], 0
	s_cbranch_scc0 .Lpfw_s0
	s_waitcnt vmcnt(6)
	s_branch .Lpfw_d0
.Lpfw_s0:
	s_waitcnt vmcnt(2)
.Lpfw_d0:
	v_mfma_f32_16x16x32_bf16 v[118:121], v[54:57], v[106:109], 0
	ds_read_b128 v[106:109], v220 offset:64
	ds_read_b128 v[138:141], v220 offset:13184
	ds_read_b128 v[134:137], v220 offset:128
	s_waitcnt lgkmcnt(7)
	v_mfma_f32_16x16x32_bf16 v[82:85], v[38:41], v[102:105], 0
	ds_read_b128 v[130:133], v220 offset:4480
	ds_read_b128 v[142:145], v220 offset:4544
	ds_read_b128 v[146:149], v220 offset:8896
	v_mfma_f32_16x16x32_bf16 v[110:113], v[42:45], v[126:129], v[110:113]
	s_lshr_b32 s2, s35, 7
	v_lshl_add_u32 v228, s31, 10, v213
	s_mov_b32 s6, 0
	s_cmp_lg_u64 s[28:29], 0
	s_cbranch_scc0 .Lpfw_s1
	s_waitcnt vmcnt(5)
	s_branch .Lpfw_d1
.Lpfw_s1:
	s_waitcnt vmcnt(1)
.Lpfw_d1:
	v_mfma_f32_16x16x32_bf16 v[118:121], v[58:61], v[126:129], v[118:121]
	ds_read_b128 v[126:129], v220 offset:8832
	s_waitcnt lgkmcnt(6)
	v_mfma_f32_16x16x32_bf16 v[82:85], v[42:45], v[106:109], v[82:85]
	v_mfma_f32_16x16x32_bf16 v[90:93], v[38:41], v[98:101], 0
	v_mfma_f32_16x16x32_bf16 v[94:97], v[38:41], v[86:89], 0
	s_waitcnt lgkmcnt(5)
	v_mfma_f32_16x16x32_bf16 v[150:153], v[46:49], v[138:141], v[110:113]
	s_cmp_lg_u64 s[28:29], 0
	s_cbranch_scc0 .Lpfw_s2
	s_waitcnt vmcnt(4)
	s_branch .Lpfw_d2

.Lpfw_d2:
	v_mfma_f32_16x16x32_bf16 v[154:157], v[62:65], v[138:141], v[118:121]
	ds_read_b128 v[138:141], v220 offset:192
	s_waitcnt lgkmcnt(5)
	v_mfma_f32_16x16x32_bf16 v[82:85], v[46:49], v[134:137], v[82:85]
	v_mfma_f32_16x16x32_bf16 v[90:93], v[42:45], v[114:117], v[90:93]
	v_mfma_f32_16x16x32_bf16 v[94:97], v[42:45], v[122:125], v[94:97]
	s_waitcnt lgkmcnt(0)
	v_mfma_f32_16x16x32_bf16 v[110:113], v[50:53], v[138:141], v[82:85]
	s_nop 3
	ds_read_b128 v[82:85], v220 offset:13248
	v_mfma_f32_16x16x32_bf16 v[90:93], v[46:49], v[130:133], v[90:93]
	v_mfma_f32_16x16x32_bf16 v[94:97], v[46:49], v[126:129], v[94:97]
	v_mfma_f32_16x16x32_bf16 v[118:121], v[50:53], v[142:145], v[90:93]
	v_mfma_f32_16x16x32_bf16 v[90:93], v[50:53], v[146:149], v[94:97]
	s_waitcnt lgkmcnt(0)
	v_mfma_f32_16x16x32_bf16 v[94:97], v[50:53], v[82:85], v[150:153]
	v_mfma_f32_16x16x32_bf16 v[82:85], v[22:25], v[82:85], v[154:157]
	ds_read_b128 v[162:165], v227
	ds_read_b128 v[158:161], v227 offset:8448
	s_nop 0
	ds_read_b128 v[154:157], v227 offset:16896
	ds_read_b128 v[150:153], v227 offset:25344
	ds_read_b128 v[230:233], v228

.LBB0_1017:
	v_pk_mul_f32 v[90:91], v[100:101], s[24:25] op_sel_hi:[1,0]
	v_pk_mul_f32 v[94:95], v[104:105], s[24:25] op_sel_hi:[1,0]
	v_pk_fma_f32 v[90:91], v[100:101], v[90:91], 1.0 op_sel_hi:[1,1,0]
	v_pk_mul_f32 v[96:97], v[102:103], s[24:25] op_sel_hi:[1,0]
	v_pk_mul_f32 v[92:93], v[98:99], s[24:25] op_sel_hi:[1,0]
	v_pk_mul_f32 v[90:91], v[100:101], v[90:91]
	v_pk_fma_f32 v[94:95], v[104:105], v[94:95], 1.0 op_sel_hi:[1,1,0]
	v_pk_fma_f32 v[96:97], v[102:103], v[96:97], 1.0 op_sel_hi:[1,1,0]
	v_pk_fma_f32 v[92:93], v[98:99], v[92:93], 1.0 op_sel_hi:[1,1,0]
	v_pk_mul_f32 v[94:95], v[104:105], v[94:95]
	v_pk_mul_f32 v[96:97], v[102:103], v[96:97]
	v_mul_f32_e32 v90, 0xc0135761, v90
	v_pk_mul_f32 v[92:93], v[98:99], v[92:93]
	v_mul_f32_e32 v96, 0xc0135761, v96
	v_exp_f32_e32 v106, v90
	v_mul_f32_e32 v90, 0xc0135761, v94
	v_mul_f32_e32 v92, 0xc0135761, v92
	v_exp_f32_e32 v96, v96
	v_mul_f32_e32 v93, 0xc0135761, v93
	v_exp_f32_e32 v107, v90
	v_mul_f32_e32 v90, 0xc0135761, v91
	v_exp_f32_e32 v92, v92
	v_exp_f32_e32 v93, v93
	v_mul_f32_e32 v97, 0xc0135761, v97
	v_exp_f32_e32 v108, v90
	v_mul_f32_e32 v90, 0xc0135761, v95
	v_exp_f32_e32 v97, v97
	v_exp_f32_e32 v109, v90
	v_add_f32_e32 v91, 1.0, v96
	v_add_f32_e32 v90, 1.0, v92
	v_rcp_f32_e32 v92, v91
	v_add_f32_e32 v91, 1.0, v93
	v_add_f32_e32 v95, 1.0, v107
	s_add_u32 s6, s26, s30
	v_rcp_f32_e32 v90, v90
	v_rcp_f32_e32 v91, v91
	v_add_f32_e32 v93, 1.0, v97
	v_add_f32_e32 v94, 1.0, v106
	v_rcp_f32_e32 v96, v95
	v_add_f32_e32 v95, 1.0, v108
	v_add_f32_e32 v97, 1.0, v109
	s_addc_u32 s7, s27, 0
	v_rcp_f32_e32 v94, v94
	v_rcp_f32_e32 v95, v95
	v_rcp_f32_e32 v97, v97
	v_rcp_f32_e32 v93, v93
	s_lshl_b64 s[6:7], s[6:7], 5
	s_add_u32 s6, s4, s6
	s_addc_u32 s7, s5, s7
	s_lshl_b32 s2, s2, 5
	v_pk_mul_f32 v[90:91], v[98:99], v[90:91]
	v_pk_mul_f32 v[94:95], v[100:101], v[94:95]
	v_pk_mul_f32 v[96:97], v[104:105], v[96:97]
	v_pk_mul_f32 v[92:93], v[102:103], v[92:93]
	v_cvt_pk_bf16_f32 v90, v90, v91
	v_cvt_pk_bf16_f32 v91, v94, v95
	v_add3_u32 v98, v214, s2, v210
	v_cvt_pk_bf16_f32 v92, v92, v93
	v_cvt_pk_bf16_f32 v93, v96, v97
	ds_write_b64 v98, v[90:91]
	ds_write_b64 v98, v[92:93] offset:8448
	v_pk_mul_f32 v[90:91], v[88:89], s[24:25] op_sel_hi:[1,0]
	v_pk_mul_f32 v[96:97], v[82:83], s[24:25] op_sel_hi:[1,0]
	v_pk_mul_f32 v[92:93], v[86:87], s[24:25] op_sel_hi:[1,0]
	v_pk_fma_f32 v[90:91], v[88:89], v[90:91], 1.0 op_sel_hi:[1,1,0]
	v_pk_mul_f32 v[94:95], v[84:85], s[24:25] op_sel_hi:[1,0]
	v_pk_fma_f32 v[96:97], v[82:83], v[96:97], 1.0 op_sel_hi:[1,1,0]
	v_pk_fma_f32 v[92:93], v[86:87], v[92:93], 1.0 op_sel_hi:[1,1,0]
	v_pk_mul_f32 v[90:91], v[88:89], v[90:91]
	v_pk_fma_f32 v[94:95], v[84:85], v[94:95], 1.0 op_sel_hi:[1,1,0]
	v_pk_mul_f32 v[96:97], v[82:83], v[96:97]
	v_pk_mul_f32 v[92:93], v[86:87], v[92:93]
	v_pk_mul_f32 v[94:95], v[84:85], v[94:95]
	v_mul_f32_e32 v96, 0xc0135761, v96
	v_mul_f32_e32 v90, 0xc0135761, v90
	v_mul_f32_e32 v92, 0xc0135761, v92
	v_exp_f32_e32 v96, v96
	v_mul_f32_e32 v93, 0xc0135761, v93
	v_exp_f32_e32 v99, v90
	v_mul_f32_e32 v90, 0xc0135761, v94
	v_exp_f32_e32 v92, v92
	v_exp_f32_e32 v93, v93
	v_mul_f32_e32 v97, 0xc0135761, v97
	v_exp_f32_e32 v100, v90
	v_mul_f32_e32 v90, 0xc0135761, v91
	v_exp_f32_e32 v97, v97
	v_exp_f32_e32 v101, v90
	v_mul_f32_e32 v90, 0xc0135761, v95
	v_exp_f32_e32 v102, v90
	v_add_f32_e32 v91, 1.0, v96
	v_add_f32_e32 v90, 1.0, v92
	v_rcp_f32_e32 v92, v91
	v_add_f32_e32 v91, 1.0, v93
	v_add_f32_e32 v95, 1.0, v100
	v_rcp_f32_e32 v90, v90
	v_rcp_f32_e32 v91, v91
	v_add_f32_e32 v93, 1.0, v97
	v_add_f32_e32 v94, 1.0, v99
	v_rcp_f32_e32 v96, v95
	v_add_f32_e32 v95, 1.0, v101
	v_rcp_f32_e32 v94, v94
	v_rcp_f32_e32 v95, v95
	v_add_f32_e32 v97, 1.0, v102
	v_rcp_f32_e32 v93, v93
	v_rcp_f32_e32 v97, v97
	v_pk_mul_f32 v[86:87], v[86:87], v[90:91]
	v_pk_mul_f32 v[88:89], v[88:89], v[94:95]
	v_pk_mul_f32 v[82:83], v[82:83], v[92:93]
	v_cvt_pk_bf16_f32 v86, v86, v87
	v_cvt_pk_bf16_f32 v87, v88, v89
	v_pk_mul_f32 v[84:85], v[84:85], v[96:97]
	v_cvt_pk_bf16_f32 v82, v82, v83
	v_lshl_add_u64 v[90:91], s[6:7], 0, v[168:169]
	v_cvt_pk_bf16_f32 v83, v84, v85
	ds_write_b64 v98, v[86:87] offset:16896
	ds_write_b64 v98, v[82:83] offset:25344
	s_waitcnt lgkmcnt(0)
	s_barrier
	v_add_u32_e32 v82, v215, v204
	ds_read_b128 v[82:85], v82
	v_add_u32_e32 v86, v215, v205
	ds_read_b128 v[86:89], v86
	v_add_co_u32_e32 v92, vcc, s12, v90
	s_waitcnt lgkmcnt(1)
	global_store_dwordx4 v168, v[82:85], s[6:7]
	v_addc_co_u32_e32 v93, vcc, 0, v91, vcc
	s_nop 0
	v_add_u32_e32 v82, v215, v206
	ds_read_b128 v[82:85], v82
	s_waitcnt lgkmcnt(1)
	global_store_dwordx4 v[92:93], v[86:89], off
	s_nop 1
	v_add_u32_e32 v86, v215, v207
	ds_read_b128 v[86:89], v86
	s_waitcnt lgkmcnt(1)
	global_store_dwordx4 v219, v[82:85], s[6:7]
	s_nop 1
	v_add_co_u32_e32 v82, vcc, 0x6000, v90
	s_nop 1
	v_addc_co_u32_e32 v83, vcc, 0, v91, vcc
	s_andn2_b64 vcc, exec, s[28:29]
	s_waitcnt lgkmcnt(0)
	global_store_dwordx4 v[82:83], v[86:89], off
	s_cbranch_vccnz .LBB0_1003
	s_waitcnt vmcnt(4)
	s_mul_i32 s38, s38, 0x8400
	v_add_u32_e32 v82, s38, v167
	v_add_u32_e32 v83, v82, v207
	v_add_u32_e32 v84, v82, v206
	v_add_u32_e32 v85, v82, v205
	v_add_u32_e32 v82, v82, v204
	ds_write_b128 v82, v[66:69]
	ds_write_b128 v85, v[70:73]
	ds_write_b128 v84, v[74:77]
	ds_write_b128 v83, v[78:81]
	s_branch .LBB0_1003
